# DK64 (GQA) latent attention inner loop restructured like DK32: K frags shared by both streams and prefetched behind a mid-iteration barrier, Q frags streamed through one register buffer, permlane32 ro
# speedup vs baseline: 1.0431x; 1.0083x over previous
; #define MFMA32(a, b, c) __builtin_amdgcn_mfma_f32_32x32x16_bf16((a), (b), (c), 0, 0, 0)
; DI float shx(float v, int lane, int m) { return __int_as_float(__builtin_amdgcn_ds_bpermute((lane ^ m) << 2, __float_as_int(v))); }
; template <int DK>
; DI void attn_item(const Params& p, int layer, int b, int hd, int qt, int ctxq, char* smem) {
;     ...
;     for (int kt = 0; kt < nkt; ++kt) {
;         const int cur = kt & 1;
;         const bf16_t* kb_ = sK + cur * 64 * 72; const bf16_t* vb_ = sV + cur * 64 * 68;
; #pragma unroll
;         for (int s = 0; s < 2; ++s) {
;             if (s == 1) {
;                 if (kt + 1 < nkt) {
; #pragma unroll
;                     for (int i = 0; i < 2; ++i) { rk[i] = *(const u32x4*)(Kg + (size_t)((kt + 1) * 64 + srow + 32 * i) * 64 + sc8); rv[i] = *(const u32x4*)(Vg + (size_t)(srow + 32 * i) * NKEY + (kt + 1) * 64 + sc8); }
;                 }
;             }
;             f32x16 x[2];
; #pragma unroll
;             for (int kb = 0; kb < 2; ++kb)
; #pragma unroll
;                 for (int i = 0; i < 16; ++i) x[kb][i] = 0.f;
;             const int kofs = DK == 32 ? 32 * s : 0;
; #pragma unroll
;             for (int ks = 0; ks < NKS; ++ks) {
;                 const bf16x8 a0 = *(const bf16x8*)(kb_ + r * 72 + kofs + 16 * ks + 8 * h), a1 = *(const bf16x8*)(kb_ + (32 + r) * 72 + kofs + 16 * ks + 8 * h);
;                 const bf16x8 qv = *(const bf16x8*)(sQ + ((s * NKS + ks) * 64 + lane) * 8);
;                 x[0] = MFMA32(a0, qv, x[0]); x[1] = MFMA32(a1, qv, x[1]);
;             }
;             float mx = x[0][0];
; #pragma unroll
;             for (int i = 1; i < 16; ++i) mx = fmaxf(mx, x[0][i]);
; #pragma unroll
;             for (int i = 0; i < 16; ++i) mx = fmaxf(mx, x[1][i]);
;             mx = fmaxf(mx, shx(mx, lane, 32));
;             if (__builtin_amdgcn_ballot_w64(mx > m_[s] + 8.f) != 0) {
;                 const float mn = fmaxf(m_[s], mx);
;                 const float al = __builtin_amdgcn_exp2f(m_[s] - mn);
;                 m_[s] = mn;
;                 l_[s] *= al;
; #pragma unroll
;                 for (int d = 0; d < 2; ++d)
; #pragma unroll
;                     for (int i = 0; i < 16; ++i) O[s][d][i] *= al;
;             }
.LBB0_145:
	s_mov_b32 s21, 0
	ds_read_b128 v[212:215], v182 offset:35840
	ds_read_b128 v[216:219], v182 offset:36864
	ds_read_b128 v[220:223], v182 offset:37888
	ds_read_b128 v[184:187], v182 offset:38912
	ds_read_b128 v[128:131], v181
	ds_read_b128 v[132:135], v181 offset:32
	ds_read_b128 v[136:139], v181 offset:64
	ds_read_b128 v[140:143], v181 offset:96
	ds_read_b128 v[144:147], v181 offset:4608
	ds_read_b128 v[148:151], v181 offset:4640
	ds_read_b128 v[152:155], v181 offset:4672
	ds_read_b128 v[192:195], v181 offset:4704
	v_lshl_add_u64 v[176:177], v[176:177], 0, v[160:161]
	v_lshl_add_u64 v[178:179], v[178:179], 0, v[160:161]
	s_mov_b64 s[8:9], 0x3000
	v_lshl_add_u64 v[178:179], v[178:179], 0, s[8:9]
	global_load_dwordx4 v[196:199], v[178:179], off offset:-4096
	global_load_dwordx4 v[200:203], v[178:179], off
	global_load_dwordx4 v[204:207], v[176:177], off offset:128
	s_mov_b64 s[8:9], 0x84000
	v_lshl_add_u64 v[176:177], v[176:177], 0, s[8:9]
	global_load_dwordx4 v[208:211], v[176:177], off offset:128
	v_mov_b32_e32 v157, v156
	v_mov_b32_e32 v173, v172
.Lat64_loop:
	s_and_b32 s8, s21, 1
	s_mul_i32 s9, s8, 0x2400
	v_add_u32_e32 v175, s9, v181
	s_mul_i32 s9, s8, 0x2200
	v_add_u32_e32 v233, s9, v159
	v_add_u32_e32 v234, 0x5800, v233
	v_add_u32_e32 v233, 0x4800, v233
	s_waitcnt lgkmcnt(0)
	v_mfma_f32_32x32x16_bf16 v[80:95], v[128:131], v[212:215], 0
	v_mfma_f32_32x32x16_bf16 v[80:95], v[132:135], v[216:219], v[80:95]
	v_mfma_f32_32x32x16_bf16 v[80:95], v[136:139], v[220:223], v[80:95]
	v_mfma_f32_32x32x16_bf16 v[80:95], v[140:143], v[184:187], v[80:95]
	v_mfma_f32_32x32x16_bf16 v[64:79], v[144:147], v[212:215], 0
	v_mfma_f32_32x32x16_bf16 v[64:79], v[148:151], v[216:219], v[64:79]
	v_mfma_f32_32x32x16_bf16 v[64:79], v[152:155], v[220:223], v[64:79]
	v_mfma_f32_32x32x16_bf16 v[64:79], v[192:195], v[184:187], v[64:79]
	ds_read_b128 v[212:215], v182 offset:39936
	ds_read_b128 v[216:219], v182 offset:40960
	ds_read_b128 v[220:223], v182 offset:41984
	ds_read_b128 v[184:187], v182 offset:43008
	ds_read2_b64 v[96:99], v233 offset0:0 offset1:2
	ds_read2_b64 v[112:115], v234 offset0:32 offset1:34
	ds_read2_b64 v[100:103], v233 offset0:4 offset1:6
	ds_read2_b64 v[116:119], v234 offset0:36 offset1:38
	ds_read2_b64 v[104:107], v233 offset0:8 offset1:10
	ds_read2_b64 v[120:123], v234 offset0:40 offset1:42
	ds_read2_b64 v[108:111], v233 offset0:12 offset1:14
	ds_read2_b64 v[124:127], v234 offset0:44 offset1:46
	v_max3_f32 v183, v80, v81, v82
	v_max3_f32 v183, v183, v83, v84
	v_max3_f32 v183, v183, v85, v86
	v_max3_f32 v183, v183, v87, v88
	v_max3_f32 v183, v183, v89, v90
	v_max3_f32 v183, v183, v91, v92
	v_max3_f32 v183, v183, v93, v94
	v_max3_f32 v227, v64, v65, v66
	v_max_f32_e32 v183, v183, v95
	v_max3_f32 v227, v227, v67, v68
	v_max3_f32 v227, v227, v69, v70
	v_max3_f32 v227, v227, v71, v72
	v_max3_f32 v227, v227, v73, v74
	v_max3_f32 v227, v227, v75, v76
	v_max3_f32 v227, v227, v77, v78
	v_max3_f32 v183, v183, v227, v79
	v_mov_b32_e32 v227, v183
	s_nop 1
	v_permlane32_swap_b32_e32 v227, v183
	s_nop 0
	v_max_f32_e32 v183, v183, v227
	v_add_f32_e32 v227, 0x41000000, v156
	v_cmp_gt_f32_e32 vcc, v183, v227
	s_cbranch_vccz .Lat64_nors0
	v_max_f32_e32 v241, v156, v183
	v_sub_f32_e32 v227, v156, v241
	v_exp_f32_e32 v227, v227
	v_mov_b32_e32 v156, v241
	v_mov_b32_e32 v157, v241
	v_mul_f32_e32 v191, v191, v227
	v_mul_f32_e32 v48, v48, v227
	v_mul_f32_e32 v49, v49, v227
	v_mul_f32_e32 v50, v50, v227
	v_mul_f32_e32 v51, v51, v227
	v_mul_f32_e32 v52, v52, v227
	v_mul_f32_e32 v53, v53, v227
	v_mul_f32_e32 v54, v54, v227
	v_mul_f32_e32 v55, v55, v227
	v_mul_f32_e32 v56, v56, v227
	v_mul_f32_e32 v57, v57, v227
	v_mul_f32_e32 v58, v58, v227
	v_mul_f32_e32 v59, v59, v227
	v_mul_f32_e32 v60, v60, v227
	v_mul_f32_e32 v61, v61, v227
	v_mul_f32_e32 v62, v62, v227
	v_mul_f32_e32 v63, v63, v227
	v_mul_f32_e32 v32, v32, v227
	v_mul_f32_e32 v33, v33, v227
	v_mul_f32_e32 v34, v34, v227
	v_mul_f32_e32 v35, v35, v227
	v_mul_f32_e32 v36, v36, v227
	v_mul_f32_e32 v37, v37, v227
	v_mul_f32_e32 v38, v38, v227
	v_mul_f32_e32 v39, v39, v227
	v_mul_f32_e32 v40, v40, v227
	v_mul_f32_e32 v41, v41, v227
	v_mul_f32_e32 v42, v42, v227
	v_mul_f32_e32 v43, v43, v227
	v_mul_f32_e32 v44, v44, v227
	v_mul_f32_e32 v45, v45, v227
	v_mul_f32_e32 v46, v46, v227
	v_mul_f32_e32 v47, v47, v227
; #define MFMA32(a, b, c) __builtin_amdgcn_mfma_f32_32x32x16_bf16((a), (b), (c), 0, 0, 0)
; DI unsigned pk_bf16(float a, float b) { f32x2 v = {a, b}; bf16v2 r = __builtin_convertvector(v, bf16v2); return __builtin_bit_cast(unsigned, r); }
; template <int DK>
; DI void attn_item(const Params& p, int layer, int b, int hd, int qt, int ctxq, char* smem) {
;     ...
;             const f32x2 mref = {m_[s], m_[s]};
;             float ps = 0.f;
; #pragma unroll
;             for (int kb = 0; kb < 2; ++kb)
; #pragma unroll
;                 for (int i2 = 0; i2 < 8; ++i2) {
;                     f32x2 t = {x[kb][2 * i2], x[kb][2 * i2 + 1]};
;                     asm("v_pk_add_f32 %0, %1, %2 neg_lo:[0,1] neg_hi:[0,1]" : "=v"(t) : "v"(t), "v"(mref));
;                     const float e0 = __builtin_amdgcn_exp2f(t.x), e1 = __builtin_amdgcn_exp2f(t.y);
;                     x[kb][2 * i2] = e0; x[kb][2 * i2 + 1] = e1; ps += e0 + e1;
;                 }
;             l_[s] += ps;
; #pragma unroll
;             for (int kb = 0; kb < 2; ++kb)
; #pragma unroll
;                 for (int st = 0; st < 2; ++st) {
;                     u32x4 w;
;                     w.x = pk_bf16(x[kb][8 * st], x[kb][8 * st + 1]); w.y = pk_bf16(x[kb][8 * st + 2], x[kb][8 * st + 3]);
;                     w.z = pk_bf16(x[kb][8 * st + 4], x[kb][8 * st + 5]); w.w = pk_bf16(x[kb][8 * st + 6], x[kb][8 * st + 7]);
;                     const bf16x8 pfr = __builtin_bit_cast(bf16x8, w);
; #pragma unroll
;                     for (int d = 0; d < 2; ++d) {
;                         const bf16_t* vp = vb_ + (32 * d + r) * 68 + 32 * kb + 16 * st + 4 * h;
;                         const s16x4 lo = *(const s16x4*)vp, hi = *(const s16x4*)(vp + 8);
;                         const bf16x8 vf = __builtin_shufflevector(lo, hi, 0, 1, 2, 3, 4, 5, 6, 7);
;                         O[s][d] = MFMA32(vf, pfr, O[s][d]);
;                     }
;                 }
;         }
;         if (kt + 1 < nkt) {
;             bf16_t* wk = sK + (cur ^ 1) * 64 * 72; bf16_t* wv = sV + (cur ^ 1) * 64 * 68;
; #pragma unroll
;             for (int i = 0; i < 2; ++i) {
;                 *(u32x4*)(wk + (srow + 32 * i) * 72 + sc8) = rk[i];
;                 *(u32x2*)(wv + (srow + 32 * i) * 68 + sc8) = (u32x2){rv[i].x, rv[i].y}; *(u32x2*)(wv + (srow + 32 * i) * 68 + sc8 + 4) = (u32x2){rv[i].z, rv[i].w};
;             }
;         }
.Lat64_nors0:
	v_pk_add_f32 v[80:81], v[80:81], v[156:157] neg_lo:[0,1] neg_hi:[0,1]
	v_pk_add_f32 v[82:83], v[82:83], v[156:157] neg_lo:[0,1] neg_hi:[0,1]
	v_pk_add_f32 v[84:85], v[84:85], v[156:157] neg_lo:[0,1] neg_hi:[0,1]
	v_pk_add_f32 v[86:87], v[86:87], v[156:157] neg_lo:[0,1] neg_hi:[0,1]
	v_exp_f32_e32 v80, v80
	v_exp_f32_e32 v81, v81
	v_exp_f32_e32 v82, v82
	v_exp_f32_e32 v83, v83
	v_exp_f32_e32 v84, v84
	v_exp_f32_e32 v85, v85
	v_exp_f32_e32 v86, v86
	v_exp_f32_e32 v87, v87
	v_add_f32_e32 v233, v80, v82
	v_add_f32_e32 v234, v81, v83
	v_add_f32_e32 v233, v233, v84
	v_add_f32_e32 v234, v234, v85
	v_add_f32_e32 v233, v233, v86
	v_add_f32_e32 v234, v234, v87
	v_cvt_pk_bf16_f32 v80, v80, v81
	v_cvt_pk_bf16_f32 v81, v82, v83
	v_cvt_pk_bf16_f32 v82, v84, v85
	v_cvt_pk_bf16_f32 v83, v86, v87
	s_waitcnt lgkmcnt(0)
	v_pk_add_f32 v[88:89], v[88:89], v[156:157] neg_lo:[0,1] neg_hi:[0,1]
	v_pk_add_f32 v[90:91], v[90:91], v[156:157] neg_lo:[0,1] neg_hi:[0,1]
	v_pk_add_f32 v[92:93], v[92:93], v[156:157] neg_lo:[0,1] neg_hi:[0,1]
	v_pk_add_f32 v[94:95], v[94:95], v[156:157] neg_lo:[0,1] neg_hi:[0,1]
	v_mfma_f32_32x32x16_bf16 v[48:63], v[96:99], v[80:83], v[48:63]
	v_mfma_f32_32x32x16_bf16 v[32:47], v[112:115], v[80:83], v[32:47]
	v_exp_f32_e32 v88, v88
	v_exp_f32_e32 v89, v89
	v_exp_f32_e32 v90, v90
	v_exp_f32_e32 v91, v91
	v_exp_f32_e32 v92, v92
	v_exp_f32_e32 v93, v93
	v_exp_f32_e32 v94, v94
	v_exp_f32_e32 v95, v95
	v_add_f32_e32 v233, v233, v88
	v_add_f32_e32 v234, v234, v89
	v_add_f32_e32 v233, v233, v90
	v_add_f32_e32 v234, v234, v91
	v_add_f32_e32 v233, v233, v92
	v_add_f32_e32 v234, v234, v93
	v_add_f32_e32 v233, v233, v94
	v_add_f32_e32 v234, v234, v95
	v_cvt_pk_bf16_f32 v88, v88, v89
	v_cvt_pk_bf16_f32 v89, v90, v91
	v_cvt_pk_bf16_f32 v90, v92, v93
	v_cvt_pk_bf16_f32 v91, v94, v95
	v_pk_add_f32 v[64:65], v[64:65], v[156:157] neg_lo:[0,1] neg_hi:[0,1]
	v_pk_add_f32 v[66:67], v[66:67], v[156:157] neg_lo:[0,1] neg_hi:[0,1]
	v_pk_add_f32 v[68:69], v[68:69], v[156:157] neg_lo:[0,1] neg_hi:[0,1]
	v_pk_add_f32 v[70:71], v[70:71], v[156:157] neg_lo:[0,1] neg_hi:[0,1]
	v_mfma_f32_32x32x16_bf16 v[48:63], v[100:103], v[88:91], v[48:63]
	v_mfma_f32_32x32x16_bf16 v[32:47], v[116:119], v[88:91], v[32:47]
	v_mfma_f32_32x32x16_bf16 v[80:95], v[128:131], v[212:215], 0
	v_mfma_f32_32x32x16_bf16 v[80:95], v[132:135], v[216:219], v[80:95]
	v_mfma_f32_32x32x16_bf16 v[80:95], v[136:139], v[220:223], v[80:95]
	v_mfma_f32_32x32x16_bf16 v[80:95], v[140:143], v[184:187], v[80:95]
	v_exp_f32_e32 v64, v64
	v_exp_f32_e32 v65, v65
	v_exp_f32_e32 v66, v66
	v_exp_f32_e32 v67, v67
	v_exp_f32_e32 v68, v68
	v_exp_f32_e32 v69, v69
	v_exp_f32_e32 v70, v70
	v_exp_f32_e32 v71, v71
	v_add_f32_e32 v233, v233, v64
	v_add_f32_e32 v234, v234, v65
	v_add_f32_e32 v233, v233, v66
	v_add_f32_e32 v234, v234, v67
	v_add_f32_e32 v233, v233, v68
	v_add_f32_e32 v234, v234, v69
	v_add_f32_e32 v233, v233, v70
	v_add_f32_e32 v234, v234, v71
	v_cvt_pk_bf16_f32 v64, v64, v65
	v_cvt_pk_bf16_f32 v65, v66, v67
	v_cvt_pk_bf16_f32 v66, v68, v69
	v_cvt_pk_bf16_f32 v67, v70, v71
	v_pk_add_f32 v[72:73], v[72:73], v[156:157] neg_lo:[0,1] neg_hi:[0,1]
	v_pk_add_f32 v[74:75], v[74:75], v[156:157] neg_lo:[0,1] neg_hi:[0,1]
	v_pk_add_f32 v[76:77], v[76:77], v[156:157] neg_lo:[0,1] neg_hi:[0,1]
	v_pk_add_f32 v[78:79], v[78:79], v[156:157] neg_lo:[0,1] neg_hi:[0,1]
	v_mfma_f32_32x32x16_bf16 v[48:63], v[104:107], v[64:67], v[48:63]
	v_mfma_f32_32x32x16_bf16 v[32:47], v[120:123], v[64:67], v[32:47]
	v_exp_f32_e32 v72, v72
	v_exp_f32_e32 v73, v73
	v_exp_f32_e32 v74, v74
	v_exp_f32_e32 v75, v75
	v_exp_f32_e32 v76, v76
	v_exp_f32_e32 v77, v77
	v_exp_f32_e32 v78, v78
	v_exp_f32_e32 v79, v79
	v_add_f32_e32 v233, v233, v72
	v_add_f32_e32 v234, v234, v73
	v_add_f32_e32 v233, v233, v74
	v_add_f32_e32 v234, v234, v75
	v_add_f32_e32 v233, v233, v76
	v_add_f32_e32 v234, v234, v77
	v_add_f32_e32 v233, v233, v78
	v_add_f32_e32 v234, v234, v79
	v_cvt_pk_bf16_f32 v72, v72, v73
	v_cvt_pk_bf16_f32 v73, v74, v75
	v_cvt_pk_bf16_f32 v74, v76, v77
	v_cvt_pk_bf16_f32 v75, v78, v79
	v_add_f32_e32 v233, v233, v234
	v_add_f32_e32 v191, v191, v233
	v_mfma_f32_32x32x16_bf16 v[48:63], v[108:111], v[72:75], v[48:63]
	v_mfma_f32_32x32x16_bf16 v[32:47], v[124:127], v[72:75], v[32:47]
	v_mfma_f32_32x32x16_bf16 v[64:79], v[144:147], v[212:215], 0
	v_mfma_f32_32x32x16_bf16 v[64:79], v[148:151], v[216:219], v[64:79]
	v_mfma_f32_32x32x16_bf16 v[64:79], v[152:155], v[220:223], v[64:79]
	v_mfma_f32_32x32x16_bf16 v[64:79], v[192:195], v[184:187], v[64:79]
	s_and_b32 s8, s21, 1
	s_xor_b32 s8, s8, 1
	s_mul_i32 s9, s8, 0x2400
	v_add_u32_e32 v183, s9, v158
	v_add_u32_e32 v175, s9, v181
	s_mul_i32 s9, s8, 0x2200
	v_add_u32_e32 v227, s9, v174
	v_add_u32_e32 v241, 0x5900, v227
	v_add_u32_e32 v227, 0x4800, v227
	s_waitcnt vmcnt(0)
	ds_write_b128 v183, v[196:199]
	ds_write_b128 v183, v[200:203] offset:4608
	ds_write2_b64 v227, v[204:205], v[206:207] offset1:1
	ds_write2_b64 v241, v[208:209], v[210:211] offset1:1
	s_cmp_lt_u32 s21, 0x82
	s_cbranch_scc0 .Lat64_skipld
	s_mov_b64 s[8:9], 0x2000
	v_lshl_add_u64 v[178:179], v[178:179], 0, s[8:9]
	s_mov_b32 s8, 0xfff7c080
	s_mov_b32 s9, -1
	v_lshl_add_u64 v[176:177], v[176:177], 0, s[8:9]
	global_load_dwordx4 v[196:199], v[178:179], off offset:-4096
	global_load_dwordx4 v[200:203], v[178:179], off
	global_load_dwordx4 v[204:207], v[176:177], off offset:128
	s_mov_b64 s[8:9], 0x84000
	v_lshl_add_u64 v[176:177], v[176:177], 0, s[8:9]
	global_load_dwordx4 v[208:211], v[176:177], off offset:128
; template <int DK>
; DI void attn_item(const Params& p, int layer, int b, int hd, int qt, int ctxq, char* smem) {
;     ...
;             float mx = x[0][0];
; #pragma unroll
;             for (int i = 1; i < 16; ++i) mx = fmaxf(mx, x[0][i]);
; #pragma unroll
;             for (int i = 0; i < 16; ++i) mx = fmaxf(mx, x[1][i]);
;             mx = fmaxf(mx, shx(mx, lane, 32));
;             if (__builtin_amdgcn_ballot_w64(mx > m_[s] + 8.f) != 0) {
;                 const float mn = fmaxf(m_[s], mx);
;                 const float al = __builtin_amdgcn_exp2f(m_[s] - mn);
;                 m_[s] = mn;
;                 l_[s] *= al;
; #pragma unroll
;                 for (int d = 0; d < 2; ++d)
; #pragma unroll
;                     for (int i = 0; i < 16; ++i) O[s][d][i] *= al;
;             }
;             const f32x2 mref = {m_[s], m_[s]};
;             float ps = 0.f;
; #pragma unroll
;             for (int kb = 0; kb < 2; ++kb)
; #pragma unroll
;                 for (int i2 = 0; i2 < 8; ++i2) {
;                     f32x2 t = {x[kb][2 * i2], x[kb][2 * i2 + 1]};
;                     asm("v_pk_add_f32 %0, %1, %2 neg_lo:[0,1] neg_hi:[0,1]" : "=v"(t) : "v"(t), "v"(mref));
;                     const float e0 = __builtin_amdgcn_exp2f(t.x), e1 = __builtin_amdgcn_exp2f(t.y);
;                     x[kb][2 * i2] = e0; x[kb][2 * i2 + 1] = e1; ps += e0 + e1;
;                 }
;             l_[s] += ps;
; #pragma unroll
;             for (int kb = 0; kb < 2; ++kb)
; #pragma unroll
;                 for (int st = 0; st < 2; ++st) {
;                     u32x4 w;
;                     w.x = pk_bf16(x[kb][8 * st], x[kb][8 * st + 1]); w.y = pk_bf16(x[kb][8 * st + 2], x[kb][8 * st + 3]);
;                     w.z = pk_bf16(x[kb][8 * st + 4], x[kb][8 * st + 5]); w.w = pk_bf16(x[kb][8 * st + 6], x[kb][8 * st + 7]);
;                     const bf16x8 pfr = __builtin_bit_cast(bf16x8, w);
; #pragma unroll
;                     for (int d = 0; d < 2; ++d) {
;                         const bf16_t* vp = vb_ + (32 * d + r) * 68 + 32 * kb + 16 * st + 4 * h;
;                         const s16x4 lo = *(const s16x4*)vp, hi = *(const s16x4*)(vp + 8);
;                         const bf16x8 vf = __builtin_shufflevector(lo, hi, 0, 1, 2, 3, 4, 5, 6, 7);
;                         O[s][d] = MFMA32(vf, pfr, O[s][d]);
;                     }
;                 }
;         }
;         if (kt + 1 < nkt) {
.Lat64_skipld:
	v_max3_f32 v183, v80, v81, v82
	v_max3_f32 v183, v183, v83, v84
	v_max3_f32 v183, v183, v85, v86
	v_max3_f32 v183, v183, v87, v88
	v_max3_f32 v183, v183, v89, v90
	v_max3_f32 v183, v183, v91, v92
	v_max3_f32 v183, v183, v93, v94
	v_max3_f32 v227, v64, v65, v66
	v_max_f32_e32 v183, v183, v95
	v_max3_f32 v227, v227, v67, v68
	v_max3_f32 v227, v227, v69, v70
	v_max3_f32 v227, v227, v71, v72
	v_max3_f32 v227, v227, v73, v74
	v_max3_f32 v227, v227, v75, v76
	v_max3_f32 v227, v227, v77, v78
	v_max3_f32 v183, v183, v227, v79
	v_mov_b32_e32 v227, v183
	s_nop 1
	v_permlane32_swap_b32_e32 v227, v183
	s_nop 0
	v_max_f32_e32 v183, v183, v227
	v_add_f32_e32 v227, 0x41000000, v172
	v_cmp_gt_f32_e32 vcc, v183, v227
	s_cbranch_vccz .Lat64_nors1
	v_max_f32_e32 v241, v172, v183
	v_sub_f32_e32 v227, v172, v241
	v_exp_f32_e32 v227, v227
	v_mov_b32_e32 v172, v241
	v_mov_b32_e32 v173, v241
	v_mul_f32_e32 v180, v180, v227
	v_mul_f32_e32 v16, v16, v227
	v_mul_f32_e32 v17, v17, v227
	v_mul_f32_e32 v18, v18, v227
	v_mul_f32_e32 v19, v19, v227
	v_mul_f32_e32 v20, v20, v227
	v_mul_f32_e32 v21, v21, v227
	v_mul_f32_e32 v22, v22, v227
	v_mul_f32_e32 v23, v23, v227
	v_mul_f32_e32 v24, v24, v227
	v_mul_f32_e32 v25, v25, v227
	v_mul_f32_e32 v26, v26, v227
	v_mul_f32_e32 v27, v27, v227
	v_mul_f32_e32 v28, v28, v227
	v_mul_f32_e32 v29, v29, v227
	v_mul_f32_e32 v30, v30, v227
	v_mul_f32_e32 v31, v31, v227
	v_mul_f32_e32 v0, v0, v227
	v_mul_f32_e32 v1, v1, v227
	v_mul_f32_e32 v2, v2, v227
	v_mul_f32_e32 v3, v3, v227
	v_mul_f32_e32 v4, v4, v227
	v_mul_f32_e32 v5, v5, v227
	v_mul_f32_e32 v6, v6, v227
	v_mul_f32_e32 v7, v7, v227
	v_mul_f32_e32 v8, v8, v227
	v_mul_f32_e32 v9, v9, v227
	v_mul_f32_e32 v10, v10, v227
	v_mul_f32_e32 v11, v11, v227
	v_mul_f32_e32 v12, v12, v227
	v_mul_f32_e32 v13, v13, v227
	v_mul_f32_e32 v14, v14, v227
	v_mul_f32_e32 v15, v15, v227
.Lat64_nors1:
	v_pk_add_f32 v[80:81], v[80:81], v[172:173] neg_lo:[0,1] neg_hi:[0,1]
	v_pk_add_f32 v[82:83], v[82:83], v[172:173] neg_lo:[0,1] neg_hi:[0,1]
	v_pk_add_f32 v[84:85], v[84:85], v[172:173] neg_lo:[0,1] neg_hi:[0,1]
	v_pk_add_f32 v[86:87], v[86:87], v[172:173] neg_lo:[0,1] neg_hi:[0,1]
	v_exp_f32_e32 v80, v80
	v_exp_f32_e32 v81, v81
	v_exp_f32_e32 v82, v82
	v_exp_f32_e32 v83, v83
	v_exp_f32_e32 v84, v84
	v_exp_f32_e32 v85, v85
	v_exp_f32_e32 v86, v86
	v_exp_f32_e32 v87, v87
	v_add_f32_e32 v233, v80, v82
	v_add_f32_e32 v234, v81, v83
	v_add_f32_e32 v233, v233, v84
	v_add_f32_e32 v234, v234, v85
	v_add_f32_e32 v233, v233, v86
	v_add_f32_e32 v234, v234, v87
	v_cvt_pk_bf16_f32 v80, v80, v81
	v_cvt_pk_bf16_f32 v81, v82, v83
	v_cvt_pk_bf16_f32 v82, v84, v85
	v_cvt_pk_bf16_f32 v83, v86, v87
	v_pk_add_f32 v[88:89], v[88:89], v[172:173] neg_lo:[0,1] neg_hi:[0,1]
	v_pk_add_f32 v[90:91], v[90:91], v[172:173] neg_lo:[0,1] neg_hi:[0,1]
	v_pk_add_f32 v[92:93], v[92:93], v[172:173] neg_lo:[0,1] neg_hi:[0,1]
	v_pk_add_f32 v[94:95], v[94:95], v[172:173] neg_lo:[0,1] neg_hi:[0,1]
	v_mfma_f32_32x32x16_bf16 v[16:31], v[96:99], v[80:83], v[16:31]
	v_mfma_f32_32x32x16_bf16 v[0:15], v[112:115], v[80:83], v[0:15]
	v_exp_f32_e32 v88, v88
	v_exp_f32_e32 v89, v89
	v_exp_f32_e32 v90, v90
	v_exp_f32_e32 v91, v91
	v_exp_f32_e32 v92, v92
	v_exp_f32_e32 v93, v93
	v_exp_f32_e32 v94, v94
	v_exp_f32_e32 v95, v95
	v_add_f32_e32 v233, v233, v88
	v_add_f32_e32 v234, v234, v89
	v_add_f32_e32 v233, v233, v90
	v_add_f32_e32 v234, v234, v91
	v_add_f32_e32 v233, v233, v92
	v_add_f32_e32 v234, v234, v93
	v_add_f32_e32 v233, v233, v94
	v_add_f32_e32 v234, v234, v95
	v_cvt_pk_bf16_f32 v88, v88, v89
	v_cvt_pk_bf16_f32 v89, v90, v91
	v_cvt_pk_bf16_f32 v90, v92, v93
	v_cvt_pk_bf16_f32 v91, v94, v95
	v_pk_add_f32 v[64:65], v[64:65], v[172:173] neg_lo:[0,1] neg_hi:[0,1]
	v_pk_add_f32 v[66:67], v[66:67], v[172:173] neg_lo:[0,1] neg_hi:[0,1]
	v_pk_add_f32 v[68:69], v[68:69], v[172:173] neg_lo:[0,1] neg_hi:[0,1]
	v_pk_add_f32 v[70:71], v[70:71], v[172:173] neg_lo:[0,1] neg_hi:[0,1]
	v_mfma_f32_32x32x16_bf16 v[16:31], v[100:103], v[88:91], v[16:31]
	v_mfma_f32_32x32x16_bf16 v[0:15], v[116:119], v[88:91], v[0:15]
	s_waitcnt lgkmcnt(0)
	s_barrier
	ds_read_b128 v[128:131], v175
	ds_read_b128 v[132:135], v175 offset:32
	ds_read_b128 v[136:139], v175 offset:64
	ds_read_b128 v[140:143], v175 offset:96
	ds_read_b128 v[144:147], v175 offset:4608
	ds_read_b128 v[148:151], v175 offset:4640
	ds_read_b128 v[152:155], v175 offset:4672
	ds_read_b128 v[192:195], v175 offset:4704
	ds_read_b128 v[212:215], v182 offset:35840
	ds_read_b128 v[216:219], v182 offset:36864
	ds_read_b128 v[220:223], v182 offset:37888
	ds_read_b128 v[184:187], v182 offset:38912
	v_exp_f32_e32 v64, v64
	v_exp_f32_e32 v65, v65
	v_exp_f32_e32 v66, v66
	v_exp_f32_e32 v67, v67
	v_exp_f32_e32 v68, v68
	v_exp_f32_e32 v69, v69
	v_exp_f32_e32 v70, v70
	v_exp_f32_e32 v71, v71
	v_add_f32_e32 v233, v233, v64
	v_add_f32_e32 v234, v234, v65
	v_add_f32_e32 v233, v233, v66
	v_add_f32_e32 v234, v234, v67
	v_add_f32_e32 v233, v233, v68
	v_add_f32_e32 v234, v234, v69
	v_add_f32_e32 v233, v233, v70
	v_add_f32_e32 v234, v234, v71
	v_cvt_pk_bf16_f32 v64, v64, v65
	v_cvt_pk_bf16_f32 v65, v66, v67
	v_cvt_pk_bf16_f32 v66, v68, v69
	v_cvt_pk_bf16_f32 v67, v70, v71
	v_pk_add_f32 v[72:73], v[72:73], v[172:173] neg_lo:[0,1] neg_hi:[0,1]
	v_pk_add_f32 v[74:75], v[74:75], v[172:173] neg_lo:[0,1] neg_hi:[0,1]
	v_pk_add_f32 v[76:77], v[76:77], v[172:173] neg_lo:[0,1] neg_hi:[0,1]
	v_pk_add_f32 v[78:79], v[78:79], v[172:173] neg_lo:[0,1] neg_hi:[0,1]
	v_mfma_f32_32x32x16_bf16 v[16:31], v[104:107], v[64:67], v[16:31]
	v_mfma_f32_32x32x16_bf16 v[0:15], v[120:123], v[64:67], v[0:15]
	v_exp_f32_e32 v72, v72
	v_exp_f32_e32 v73, v73
	v_exp_f32_e32 v74, v74
	v_exp_f32_e32 v75, v75
	v_exp_f32_e32 v76, v76
	v_exp_f32_e32 v77, v77
	v_exp_f32_e32 v78, v78
	v_exp_f32_e32 v79, v79
	v_add_f32_e32 v233, v233, v72
	v_add_f32_e32 v234, v234, v73
	v_add_f32_e32 v233, v233, v74
	v_add_f32_e32 v234, v234, v75
	v_add_f32_e32 v233, v233, v76
	v_add_f32_e32 v234, v234, v77
	v_add_f32_e32 v233, v233, v78
	v_add_f32_e32 v234, v234, v79
	v_cvt_pk_bf16_f32 v72, v72, v73
	v_cvt_pk_bf16_f32 v73, v74, v75
	v_cvt_pk_bf16_f32 v74, v76, v77
	v_cvt_pk_bf16_f32 v75, v78, v79
	v_add_f32_e32 v233, v233, v234
	v_add_f32_e32 v180, v180, v233
	v_mfma_f32_32x32x16_bf16 v[16:31], v[108:111], v[72:75], v[16:31]
	v_mfma_f32_32x32x16_bf16 v[0:15], v[124:127], v[72:75], v[0:15]
	s_add_i32 s21, s21, 1
	s_cmpk_eq_i32 s21, 0x83
	s_cbranch_scc0 .Lat64_loop
	s_waitcnt lgkmcnt(0)
